# fox attention main loop: 6-deep software-pipelined LDS fragment reads for QK/PV MFMA sections (on top of gemm saddr)
# baseline (speedup 1.0000x reference)
.LBB0_681:
	v_lshl_add_u64 v[2:3], v[154:155], 0, s[10:11]
	v_lshl_add_u64 v[6:7], v[156:157], 0, s[10:11]
	v_lshl_add_u64 v[10:11], v[152:153], 0, s[10:11]
	v_lshl_add_u64 v[14:15], v[158:159], 0, s[10:11]
	global_load_dwordx4 v[2:5], v[2:3], off
	s_andn2_b64 vcc, exec, s[70:71]
	global_load_dwordx4 v[6:9], v[6:7], off
	s_nop 0
	global_load_dwordx4 v[10:13], v[10:11], off
	s_nop 0
	global_load_dwordx4 v[144:147], v[14:15], off
	s_cbranch_vccnz .LBB0_683
	s_mul_i32 s20, s73, 0x4800
	v_add_u32_e32 v0, s20, v162
	ds_read_b128 v[206:209], v0 offset:43520
	ds_read_b128 v[210:213], v0 offset:43552
	ds_read_b128 v[214:217], v0 offset:43584
	ds_read_b128 v[218:221], v0 offset:43616
	ds_read_b128 v[222:225], v0 offset:48128
	ds_read_b128 v[226:229], v0 offset:48160
	s_waitcnt lgkmcnt(5)
	v_mfma_f32_32x32x16_bf16 v[64:79], v[206:209], v[80:83], v[64:79]
	ds_read_b128 v[206:209], v0 offset:48192
	s_waitcnt lgkmcnt(5)
	v_mfma_f32_32x32x16_bf16 v[64:79], v[210:213], v[84:87], v[64:79]
	ds_read_b128 v[210:213], v0 offset:48224
	s_waitcnt lgkmcnt(5)
	v_mfma_f32_32x32x16_bf16 v[64:79], v[214:217], v[88:91], v[64:79]
	ds_read_b128 v[214:217], v0 offset:52736
	s_waitcnt lgkmcnt(5)
	v_mfma_f32_32x32x16_bf16 v[64:79], v[218:221], v[92:95], v[64:79]
	ds_read_b128 v[218:221], v0 offset:52768
	s_waitcnt lgkmcnt(5)
	v_mfma_f32_32x32x16_bf16 v[48:63], v[222:225], v[80:83], v[48:63]
	ds_read_b128 v[222:225], v0 offset:52800
	s_waitcnt lgkmcnt(5)
	v_mfma_f32_32x32x16_bf16 v[48:63], v[226:229], v[84:87], v[48:63]
	ds_read_b128 v[226:229], v0 offset:52832
	s_waitcnt lgkmcnt(5)
	v_mfma_f32_32x32x16_bf16 v[48:63], v[206:209], v[88:91], v[48:63]
	ds_read_b128 v[206:209], v0 offset:57344
	s_waitcnt lgkmcnt(5)
	v_mfma_f32_32x32x16_bf16 v[48:63], v[210:213], v[92:95], v[48:63]
	ds_read_b128 v[210:213], v0 offset:57376
	s_waitcnt lgkmcnt(5)
	v_mfma_f32_32x32x16_bf16 v[32:47], v[214:217], v[80:83], v[32:47]
	ds_read_b128 v[214:217], v0 offset:57408
	s_waitcnt lgkmcnt(5)
	v_mfma_f32_32x32x16_bf16 v[32:47], v[218:221], v[84:87], v[32:47]
	ds_read_b128 v[218:221], v0 offset:57440
	s_waitcnt lgkmcnt(5)
	v_mfma_f32_32x32x16_bf16 v[32:47], v[222:225], v[88:91], v[32:47]
	s_waitcnt lgkmcnt(4)
	v_mfma_f32_32x32x16_bf16 v[32:47], v[226:229], v[92:95], v[32:47]
	s_waitcnt lgkmcnt(3)
	v_mfma_f32_32x32x16_bf16 v[16:31], v[206:209], v[80:83], v[16:31]
	s_waitcnt lgkmcnt(2)
	v_mfma_f32_32x32x16_bf16 v[16:31], v[210:213], v[84:87], v[16:31]
	s_waitcnt lgkmcnt(1)
	v_mfma_f32_32x32x16_bf16 v[16:31], v[214:217], v[88:91], v[16:31]
	s_waitcnt lgkmcnt(0)
	v_mfma_f32_32x32x16_bf16 v[16:31], v[218:221], v[92:95], v[16:31]
.LBB0_683:
	s_and_b32 s79, s18, 1
	s_cmp_gt_i32 s78, s77
	s_cbranch_scc1 .LBB0_692
	s_mul_i32 s20, s79, 0x4400
	ds_read_b128 v[80:83], v172
	ds_read_b128 v[84:87], v172 offset:16
	ds_read_b128 v[88:91], v172 offset:64
	ds_read_b128 v[92:95], v172 offset:80
	v_add_u32_e32 v0, s20, v164
	ds_read_b128 v[206:209], v0 offset:8704
	ds_read_b128 v[210:213], v0 offset:8736
	ds_read_b128 v[214:217], v0 offset:8768
	ds_read_b128 v[218:221], v0 offset:8800
	ds_read_b128 v[222:225], v0 offset:8832
	ds_read_b128 v[226:229], v0 offset:8864
	s_waitcnt lgkmcnt(6)
	v_xor_b32_e32 v80, 0x80000000, v80
	v_xor_b32_e32 v81, 0x80000000, v81
	v_xor_b32_e32 v82, 0x80000000, v82
	v_xor_b32_e32 v83, 0x80000000, v83
	v_xor_b32_e32 v84, 0x80000000, v84
	v_xor_b32_e32 v85, 0x80000000, v85
	v_xor_b32_e32 v86, 0x80000000, v86
	v_xor_b32_e32 v87, 0x80000000, v87
	v_xor_b32_e32 v88, 0x80000000, v88
	v_xor_b32_e32 v89, 0x80000000, v89
	v_xor_b32_e32 v90, 0x80000000, v90
	v_xor_b32_e32 v91, 0x80000000, v91
	v_xor_b32_e32 v92, 0x80000000, v92
	v_xor_b32_e32 v93, 0x80000000, v93
	v_xor_b32_e32 v94, 0x80000000, v94
	v_xor_b32_e32 v95, 0x80000000, v95
	s_add_i32 s20, s78, 63
	s_cmp_ge_i32 s20, s75
	s_mov_b64 s[56:57], -1
	s_waitcnt lgkmcnt(5)
	v_mfma_f32_32x32x16_bf16 v[80:95], v[206:209], v[140:143], v[80:95]
	ds_read_b128 v[206:209], v0 offset:8896
	s_waitcnt lgkmcnt(5)
	v_mfma_f32_32x32x16_bf16 v[80:95], v[210:213], v[136:139], v[80:95]
	ds_read_b128 v[210:213], v0 offset:8928
	ds_read_b128 v[96:99], v172 offset:128
	ds_read_b128 v[100:103], v172 offset:144
	ds_read_b128 v[104:107], v172 offset:192
	ds_read_b128 v[108:111], v172 offset:208
	s_waitcnt lgkmcnt(9)
	v_mfma_f32_32x32x16_bf16 v[80:95], v[214:217], v[132:135], v[80:95]
	ds_read_b128 v[214:217], v0 offset:17408
	s_waitcnt lgkmcnt(9)
	v_mfma_f32_32x32x16_bf16 v[80:95], v[218:221], v[128:131], v[80:95]
	ds_read_b128 v[218:221], v0 offset:17440
	s_waitcnt lgkmcnt(9)
	v_mfma_f32_32x32x16_bf16 v[80:95], v[222:225], v[124:127], v[80:95]
	ds_read_b128 v[222:225], v0 offset:17472
	s_waitcnt lgkmcnt(9)
	v_mfma_f32_32x32x16_bf16 v[80:95], v[226:229], v[120:123], v[80:95]
	ds_read_b128 v[226:229], v0 offset:17504
	s_waitcnt lgkmcnt(9)
	v_mfma_f32_32x32x16_bf16 v[80:95], v[206:209], v[116:119], v[80:95]
	ds_read_b128 v[206:209], v0 offset:17536
	s_waitcnt lgkmcnt(9)
	v_mfma_f32_32x32x16_bf16 v[80:95], v[210:213], v[112:115], v[80:95]
	ds_read_b128 v[210:213], v0 offset:17568
	s_waitcnt lgkmcnt(6)
	v_xor_b32_e32 v96, 0x80000000, v96
	v_xor_b32_e32 v97, 0x80000000, v97
	v_xor_b32_e32 v98, 0x80000000, v98
	v_xor_b32_e32 v99, 0x80000000, v99
	v_xor_b32_e32 v100, 0x80000000, v100
	v_xor_b32_e32 v101, 0x80000000, v101
	v_xor_b32_e32 v102, 0x80000000, v102
	v_xor_b32_e32 v103, 0x80000000, v103
	v_xor_b32_e32 v104, 0x80000000, v104
	v_xor_b32_e32 v105, 0x80000000, v105
	v_xor_b32_e32 v106, 0x80000000, v106
	v_xor_b32_e32 v107, 0x80000000, v107
	v_xor_b32_e32 v108, 0x80000000, v108
	v_xor_b32_e32 v109, 0x80000000, v109
	v_xor_b32_e32 v110, 0x80000000, v110
	v_xor_b32_e32 v111, 0x80000000, v111
	v_mov_b32_e32 v15, v80
	v_mov_b32_e32 v178, v85
	s_waitcnt lgkmcnt(5)
	v_mfma_f32_32x32x16_bf16 v[96:111], v[214:217], v[140:143], v[96:111]
	ds_read_b128 v[214:217], v0 offset:17600
	v_mov_b32_e32 v180, v86
	v_mov_b32_e32 v181, v87
	v_mov_b32_e32 v179, v88
	v_mov_b32_e32 v182, v89
	v_mov_b32_e32 v183, v90
	v_mov_b32_e32 v184, v91
	s_waitcnt lgkmcnt(5)
	v_mfma_f32_32x32x16_bf16 v[96:111], v[218:221], v[136:139], v[96:111]
	ds_read_b128 v[218:221], v0 offset:17632
	v_mov_b32_e32 v185, v92
	v_mov_b32_e32 v186, v93
	v_mov_b32_e32 v187, v94
	v_mov_b32_e32 v189, v95
	s_waitcnt lgkmcnt(5)
	v_mfma_f32_32x32x16_bf16 v[96:111], v[222:225], v[132:135], v[96:111]
	s_waitcnt lgkmcnt(4)
	v_mfma_f32_32x32x16_bf16 v[96:111], v[226:229], v[128:131], v[96:111]
	s_waitcnt lgkmcnt(3)
	v_mfma_f32_32x32x16_bf16 v[96:111], v[206:209], v[124:127], v[96:111]
	s_waitcnt lgkmcnt(2)
	v_mfma_f32_32x32x16_bf16 v[96:111], v[210:213], v[120:123], v[96:111]
	s_waitcnt lgkmcnt(1)
	v_mfma_f32_32x32x16_bf16 v[96:111], v[214:217], v[116:119], v[96:111]
	s_waitcnt lgkmcnt(0)
	v_mfma_f32_32x32x16_bf16 v[96:111], v[218:221], v[112:115], v[96:111]
	v_mov_b32_e32 v174, v81
	v_mov_b32_e32 v175, v82
	v_mov_b32_e32 v176, v83
	v_mov_b32_e32 v177, v84
	s_nop 7
	v_mov_b32_e32 v188, v96
	v_mov_b32_e32 v191, v97
	v_mov_b32_e32 v192, v98
	v_mov_b32_e32 v193, v99
	v_mov_b32_e32 v194, v100
	v_mov_b32_e32 v195, v101
	v_mov_b32_e32 v198, v102
	v_mov_b32_e32 v199, v103
	v_mov_b32_e32 v196, v104
	v_mov_b32_e32 v197, v105
	v_mov_b32_e32 v200, v106
	v_mov_b32_e32 v201, v107
	v_mov_b32_e32 v202, v108
	v_mov_b32_e32 v203, v109
	v_mov_b32_e32 v204, v110
	v_mov_b32_e32 v205, v111
	s_cbranch_scc0 .LBB0_686
	v_add_u32_e32 v0, s78, v148
	v_cmp_le_i32_e32 vcc, v0, v163
	v_add_u32_e32 v175, 2, v0
	v_add_u32_e32 v176, 3, v0
	v_cndmask_b32_e32 v15, v239, v80, vcc
	v_cmp_lt_i32_e32 vcc, v0, v163
	v_add_u32_e32 v177, 4, v0
	v_add_u32_e32 v178, 5, v0
	v_cndmask_b32_e32 v174, v239, v81, vcc
	v_cmp_le_i32_e32 vcc, v175, v163
	v_add_u32_e32 v179, 6, v0
	v_add_u32_e32 v182, 17, v0
	v_cndmask_b32_e32 v175, v239, v82, vcc
	v_cmp_le_i32_e32 vcc, v176, v163
	v_add_u32_e32 v183, 18, v0
	v_add_u32_e32 v184, 19, v0
	v_cndmask_b32_e32 v176, v239, v83, vcc
	v_cmp_le_i32_e32 vcc, v177, v163
	v_add_u32_e32 v185, 20, v0
	v_add_u32_e32 v186, 21, v0
	v_cndmask_b32_e32 v177, v239, v84, vcc
	v_cmp_le_i32_e32 vcc, v178, v163
	v_add_u32_e32 v187, 22, v0
	v_add_u32_e32 v188, 23, v0
	v_cndmask_b32_e32 v178, v239, v85, vcc
	v_cmp_le_i32_e32 vcc, v179, v163
	v_add_u32_e32 v179, 7, v0
	v_add_u32_e32 v191, 33, v0
	v_cndmask_b32_e32 v180, v239, v86, vcc
	v_cmp_le_i32_e32 vcc, v179, v163
	v_add_u32_e32 v179, 16, v0
	v_add_u32_e32 v192, 34, v0
	v_cndmask_b32_e32 v181, v239, v87, vcc
	v_cmp_le_i32_e32 vcc, v179, v163
	v_max3_f32 v14, v15, s23, v174
	v_add_u32_e32 v193, 35, v0
	v_cndmask_b32_e32 v179, v239, v88, vcc
	v_cmp_le_i32_e32 vcc, v182, v163
	v_max3_f32 v14, v14, v175, v176
	v_add_u32_e32 v194, 36, v0
	v_cndmask_b32_e32 v182, v239, v89, vcc
	v_cmp_le_i32_e32 vcc, v183, v163
	v_max3_f32 v14, v14, v177, v178
	v_add_u32_e32 v195, 37, v0
	v_cndmask_b32_e32 v183, v239, v90, vcc
	v_cmp_le_i32_e32 vcc, v184, v163
	v_max3_f32 v14, v14, v180, v181
	v_add_u32_e32 v196, 38, v0
	v_cndmask_b32_e32 v184, v239, v91, vcc
	v_cmp_le_i32_e32 vcc, v185, v163
	v_max3_f32 v14, v14, v179, v182
	v_max3_f32 v14, v14, v183, v184
	v_cndmask_b32_e32 v185, v239, v92, vcc
	v_cmp_le_i32_e32 vcc, v186, v163
	v_add_u32_e32 v197, 49, v0
	v_add_u32_e32 v200, 50, v0
	v_cndmask_b32_e32 v186, v239, v93, vcc
	v_cmp_le_i32_e32 vcc, v187, v163
	v_max3_f32 v14, v14, v185, v186
	v_add_u32_e32 v201, 51, v0
	v_cndmask_b32_e32 v187, v239, v94, vcc
	v_cmp_le_i32_e32 vcc, v188, v163
	v_add_u32_e32 v188, 32, v0
	v_add_u32_e32 v202, 52, v0
	v_cndmask_b32_e32 v189, v239, v95, vcc
	v_cmp_le_i32_e32 vcc, v188, v163
	v_max3_f32 v14, v14, v187, v189
	v_add_u32_e32 v203, 53, v0
	v_cndmask_b32_e32 v188, v239, v96, vcc
	v_cmp_le_i32_e32 vcc, v191, v163
	v_add_u32_e32 v204, 54, v0
	s_mov_b64 s[56:57], 0
	v_cndmask_b32_e32 v191, v239, v97, vcc
	v_cmp_le_i32_e32 vcc, v192, v163
	v_max3_f32 v14, v14, v188, v191
	s_nop 0
	v_cndmask_b32_e32 v192, v239, v98, vcc
	v_cmp_le_i32_e32 vcc, v193, v163
	s_nop 1
	v_cndmask_b32_e32 v193, v239, v99, vcc
	v_cmp_le_i32_e32 vcc, v194, v163
	v_max3_f32 v14, v14, v192, v193
	s_nop 0
	v_cndmask_b32_e32 v194, v239, v100, vcc
	v_cmp_le_i32_e32 vcc, v195, v163
	s_nop 1
	v_cndmask_b32_e32 v195, v239, v101, vcc
	v_cmp_le_i32_e32 vcc, v196, v163
	v_add_u32_e32 v196, 39, v0
	v_max3_f32 v14, v14, v194, v195
	v_cndmask_b32_e32 v198, v239, v102, vcc
	v_cmp_le_i32_e32 vcc, v196, v163
	v_add_u32_e32 v196, 48, v0
	v_add_u32_e32 v0, 55, v0
	v_cndmask_b32_e32 v199, v239, v103, vcc
	v_cmp_le_i32_e32 vcc, v196, v163
	v_max3_f32 v14, v14, v198, v199
	s_nop 0
	v_cndmask_b32_e32 v196, v239, v104, vcc
	v_cmp_le_i32_e32 vcc, v197, v163
	s_nop 1
	v_cndmask_b32_e32 v197, v239, v105, vcc
	v_cmp_le_i32_e32 vcc, v200, v163
	v_max3_f32 v14, v14, v196, v197
	s_nop 0
	v_cndmask_b32_e32 v200, v239, v106, vcc
	v_cmp_le_i32_e32 vcc, v201, v163
	s_nop 1
	v_cndmask_b32_e32 v201, v239, v107, vcc
	v_cmp_le_i32_e32 vcc, v202, v163
	v_max3_f32 v14, v14, v200, v201
	s_nop 0
	v_cndmask_b32_e32 v202, v239, v108, vcc
	v_cmp_le_i32_e32 vcc, v203, v163
	s_nop 1
	v_cndmask_b32_e32 v203, v239, v109, vcc
	v_cmp_le_i32_e32 vcc, v204, v163
	v_max3_f32 v14, v14, v202, v203
	s_nop 0
	v_cndmask_b32_e32 v204, v239, v110, vcc
	v_cmp_le_i32_e32 vcc, v0, v163
	s_nop 1
	v_cndmask_b32_e32 v205, v239, v111, vcc
	v_max3_f32 v0, v14, v204, v205

.LBB0_690:
	v_sub_f32_e32 v80, v174, v14
	v_exp_f32_e32 v96, v80
	v_sub_f32_e32 v80, v175, v14
	v_exp_f32_e32 v97, v80
	v_sub_f32_e32 v80, v176, v14
	v_exp_f32_e32 v98, v80
	v_sub_f32_e32 v80, v177, v14
	v_exp_f32_e32 v99, v80
	v_sub_f32_e32 v80, v178, v14
	v_sub_f32_e32 v84, v179, v14
	v_sub_f32_e32 v88, v188, v14
	v_sub_f32_e32 v92, v196, v14
	v_exp_f32_e32 v100, v80
	v_sub_f32_e32 v80, v180, v14
	v_exp_f32_e32 v103, v84
	v_sub_f32_e32 v84, v182, v14
	v_exp_f32_e32 v111, v88
	v_sub_f32_e32 v88, v191, v14
	v_exp_f32_e32 v180, v92
	v_sub_f32_e32 v92, v197, v14
	v_exp_f32_e32 v101, v80
	v_sub_f32_e32 v80, v181, v14
	v_exp_f32_e32 v104, v84
	v_sub_f32_e32 v84, v183, v14
	v_exp_f32_e32 v173, v88
	v_sub_f32_e32 v88, v192, v14
	v_exp_f32_e32 v181, v92
	v_sub_f32_e32 v92, v200, v14
	v_exp_f32_e32 v105, v84
	v_sub_f32_e32 v84, v184, v14
	v_exp_f32_e32 v174, v88
	v_sub_f32_e32 v88, v193, v14
	v_exp_f32_e32 v182, v92
	v_sub_f32_e32 v92, v201, v14
	v_exp_f32_e32 v106, v84
	v_sub_f32_e32 v84, v185, v14
	v_exp_f32_e32 v175, v88
	v_sub_f32_e32 v88, v194, v14
	v_exp_f32_e32 v183, v92
	v_sub_f32_e32 v92, v202, v14
	v_exp_f32_e32 v107, v84
	v_sub_f32_e32 v84, v186, v14
	v_exp_f32_e32 v176, v88
	v_sub_f32_e32 v88, v195, v14
	v_exp_f32_e32 v184, v92
	v_sub_f32_e32 v92, v203, v14
	v_exp_f32_e32 v108, v84
	v_sub_f32_e32 v84, v187, v14
	v_exp_f32_e32 v177, v88
	v_sub_f32_e32 v88, v198, v14
	v_exp_f32_e32 v185, v92
	v_sub_f32_e32 v92, v204, v14
	v_sub_f32_e32 v15, v15, v14
	v_exp_f32_e32 v109, v84
	v_sub_f32_e32 v84, v189, v14
	v_exp_f32_e32 v178, v88
	v_sub_f32_e32 v88, v199, v14
	v_exp_f32_e32 v186, v92
	v_sub_f32_e32 v92, v205, v14
	v_exp_f32_e32 v15, v15
	v_exp_f32_e32 v102, v80
	v_exp_f32_e32 v110, v84
	v_exp_f32_e32 v179, v88
	v_exp_f32_e32 v187, v92
	v_cvt_pk_bf16_f32 v80, v15, v96
	v_cvt_pk_bf16_f32 v81, v97, v98
	v_cvt_pk_bf16_f32 v82, v99, v100
	v_cvt_pk_bf16_f32 v83, v101, v102
	v_cvt_pk_bf16_f32 v84, v103, v104
	v_cvt_pk_bf16_f32 v85, v105, v106
	v_cvt_pk_bf16_f32 v86, v107, v108
	v_cvt_pk_bf16_f32 v87, v109, v110
	v_cvt_pk_bf16_f32 v88, v111, v173
	v_cvt_pk_bf16_f32 v89, v174, v175
	v_cvt_pk_bf16_f32 v90, v176, v177
	v_cvt_pk_bf16_f32 v91, v178, v179
	v_cvt_pk_bf16_f32 v92, v180, v181
	v_cvt_pk_bf16_f32 v93, v182, v183
	v_cvt_pk_bf16_f32 v94, v184, v185
	v_cvt_pk_bf16_f32 v95, v186, v187
	s_andn2_b64 vcc, exec, s[52:53]
	s_mov_b64 s[70:71], -1
	s_cbranch_vccnz .LBB0_693
	s_mul_i32 s20, s74, 0x4800
	v_add_u32_e32 v188, s20, v162
	s_mov_b64 s[70:71], 0
	ds_read_b128 v[206:209], v188 offset:43520
	ds_read_b128 v[210:213], v188 offset:43552
	ds_read_b128 v[214:217], v188 offset:43584
	ds_read_b128 v[218:221], v188 offset:43616
	ds_read_b128 v[222:225], v188 offset:48128
	ds_read_b128 v[226:229], v188 offset:48160
	s_waitcnt lgkmcnt(5)
	v_mfma_f32_32x32x16_bf16 v[64:79], v[206:209], v[80:83], v[64:79]
	ds_read_b128 v[206:209], v188 offset:48192
	s_waitcnt lgkmcnt(5)
	v_mfma_f32_32x32x16_bf16 v[64:79], v[210:213], v[84:87], v[64:79]
	ds_read_b128 v[210:213], v188 offset:48224
	s_waitcnt lgkmcnt(5)
	v_mfma_f32_32x32x16_bf16 v[64:79], v[214:217], v[88:91], v[64:79]
	ds_read_b128 v[214:217], v188 offset:52736
	s_waitcnt lgkmcnt(5)
	v_mfma_f32_32x32x16_bf16 v[64:79], v[218:221], v[92:95], v[64:79]
	ds_read_b128 v[218:221], v188 offset:52768
	s_waitcnt lgkmcnt(5)
	v_mfma_f32_32x32x16_bf16 v[48:63], v[222:225], v[80:83], v[48:63]
	ds_read_b128 v[222:225], v188 offset:52800
	s_waitcnt lgkmcnt(5)
	v_mfma_f32_32x32x16_bf16 v[48:63], v[226:229], v[84:87], v[48:63]
	ds_read_b128 v[226:229], v188 offset:52832
	s_waitcnt lgkmcnt(5)
	v_mfma_f32_32x32x16_bf16 v[48:63], v[206:209], v[88:91], v[48:63]
	ds_read_b128 v[206:209], v188 offset:57344
	s_waitcnt lgkmcnt(5)
	v_mfma_f32_32x32x16_bf16 v[48:63], v[210:213], v[92:95], v[48:63]
	ds_read_b128 v[210:213], v188 offset:57376
	s_waitcnt lgkmcnt(5)
	v_mfma_f32_32x32x16_bf16 v[32:47], v[214:217], v[80:83], v[32:47]
	ds_read_b128 v[214:217], v188 offset:57408
	s_waitcnt lgkmcnt(5)
	v_mfma_f32_32x32x16_bf16 v[32:47], v[218:221], v[84:87], v[32:47]
	ds_read_b128 v[218:221], v188 offset:57440
	s_waitcnt lgkmcnt(5)
	v_mfma_f32_32x32x16_bf16 v[32:47], v[222:225], v[88:91], v[32:47]
	s_waitcnt lgkmcnt(4)
	v_mfma_f32_32x32x16_bf16 v[32:47], v[226:229], v[92:95], v[32:47]
	s_waitcnt lgkmcnt(3)
	v_mfma_f32_32x32x16_bf16 v[16:31], v[206:209], v[80:83], v[16:31]
	s_waitcnt lgkmcnt(2)
	v_mfma_f32_32x32x16_bf16 v[16:31], v[210:213], v[84:87], v[16:31]
	s_waitcnt lgkmcnt(1)
	v_mfma_f32_32x32x16_bf16 v[16:31], v[214:217], v[88:91], v[16:31]
	s_waitcnt lgkmcnt(0)
	v_mfma_f32_32x32x16_bf16 v[16:31], v[218:221], v[92:95], v[16:31]
	s_branch .LBB0_694
